# pair8l plus a second s_barrier per x-packer block (before the bf16 / fp4 stores) and a second one per P6 row (before the output stores)
# baseline (speedup 1.0000x reference)
; #define LAS __attribute__((address_space(3)))
; #define LDS_WAIT() asm volatile("s_waitcnt lgkmcnt(0)" ::: "memory")
; __device__ __forceinline__ unsigned pk2(float lo, float hi) { return cvt_pk_bf16(lo, hi); }
; #define XLOAD(blk_) do { const size_t e0_ = (blk_) * 2048; const float* s0_ = (e0_ < (size_t)SEQ * DM) ? F.xp + e0_ : F.xs + (e0_ - (size_t)SEQ * DM); \
;     _Pragma("unroll") for (int i = 0; i < 4; ++i) { const float* s_ = s0_ + (i * 64 + plane) * 8; la[i] = *(const f32x4*)s_; lb[i] = *(const f32x4*)(s_ + 4); } } while (0)
;     __device__ __forceinline__ unsigned a(const pg8::Unit& u) const { return (unsigned)u.pm * (256u * K * 2u); }
;     __device__ __forceinline__ unsigned a(const pg8::Unit& u) const { return (unsigned)u.pm * (256u * K * 2u); }
;     __device__ __forceinline__ unsigned a(const pg8::Unit& u) const { return (unsigned)u.pm * (256u * K * 2u); }
;     __device__ __forceinline__ unsigned a(const pg8::Unit& u) const { return (unsigned)u.pm * (256u * K * 2u); }
;     __device__ __forceinline__ unsigned a(const pg8::Unit& u) const { return (unsigned)u.pm * (256u * K * 2u); }
; __device__ __forceinline__ void p0_prologue(const Frame& F) {
;     ...
;         for (; blk < NB; blk += NGW) {
;             const size_t e0 = blk * 2048;
;             f32x4 a[4], b[4];
; #pragma unroll
;             for (int i = 0; i < 4; ++i) { a[i] = la[i]; b[i] = lb[i]; }
;             if (blk + NGW < NB) XLOAD(blk + NGW);
; #pragma unroll
;             for (int i = 0; i < 4; ++i) {
;                 const int p8 = i * 64 + plane; const size_t e = e0 + (size_t)p8 * 8;
;                 u32x4 w; w.x = pk2(a[i][0], a[i][1]); w.y = pk2(a[i][2], a[i][3]); w.z = pk2(b[i][0], b[i][1]); w.w = pk2(b[i][2], b[i][3]);
;                 *(u32x4*)(F.XB + e) = w;
;                 const float xv[8] = {a[i][0], a[i][1], a[i][2], a[i][3], b[i][0], b[i][1], b[i][2], b[i][3]};
;                 *(unsigned*)(F.XB4 + e / 2) = q4x8(xv, X4_SCALE);
;                 LAS float* d = scr + (p8 >> 2) * 36 + (p8 & 3) * 8;
;                 *(LAS f32x4*)d = a[i]; *(LAS f32x4*)(d + 4) = b[i];
;             }
;             LDS_WAIT(); asm volatile("" ::: "memory");
.LBB0_51:
	s_barrier
	v_cvt_pk_bf16_f32 v86, v28, v29
	v_cvt_pk_bf16_f32 v87, v30, v31
	v_cvt_pk_bf16_f32 v88, v24, v25
	v_cvt_pk_bf16_f32 v89, v26, v27
	v_add_f32_e32 v33, v28, v28
	v_add_f32_e32 v69, v29, v29
	global_store_dwordx4 v[72:73], v[86:89], off offset:-2048
	v_med3_f32 v33, v33, s35, v84
	v_med3_f32 v69, v69, s35, v84
	v_mov_b32_e32 v88, 0
	v_cvt_scalef32_pk_fp4_f32 v88, v33, v69, 1.0
	v_add_f32_e32 v33, v30, v30
	v_add_f32_e32 v69, v31, v31
	v_med3_f32 v33, v33, s35, v84
	v_med3_f32 v69, v69, s35, v84
	v_cvt_scalef32_pk_fp4_f32 v88, v33, v69, 1.0 op_sel:[0,0,1,0]
	v_add_f32_e32 v33, v24, v24
	v_add_f32_e32 v69, v25, v25
	v_med3_f32 v33, v33, s35, v84
	v_med3_f32 v69, v69, s35, v84
	v_lshl_add_u64 v[90:91], s[4:5], 0, v[78:79]
	v_cvt_scalef32_pk_fp4_f32 v88, v33, v69, 1.0 op_sel:[0,0,0,1]
	v_add_f32_e32 v33, v26, v26
	v_add_f32_e32 v69, v27, v27
	v_med3_f32 v33, v33, s35, v84
	v_med3_f32 v69, v69, s35, v84
	v_lshrrev_b64 v[86:87], 1, v[90:91]
	v_cvt_scalef32_pk_fp4_f32 v88, v33, v69, 1.0 op_sel:[0,0,1,1]
	v_lshl_add_u64 v[86:87], s[52:53], 0, v[86:87]
	global_store_dword v[86:87], v88, off
	ds_write_b128 v67, v[28:31]
	ds_write_b128 v67, v[24:27] offset:16
	v_cvt_pk_bf16_f32 v24, v20, v21
	v_cvt_pk_bf16_f32 v25, v22, v23
	v_cvt_pk_bf16_f32 v26, v16, v17
	v_cvt_pk_bf16_f32 v27, v18, v19
	global_store_dwordx4 v[72:73], v[24:27], off offset:-1024
	v_lshl_add_u64 v[28:29], v[90:91], 0, s[68:69]
	v_lshl_add_u64 v[86:87], v[70:71], 0, s[4:5]
	v_add_f32_e32 v24, v20, v20
	v_add_f32_e32 v25, v21, v21
	v_med3_f32 v24, v24, s35, v84
	v_med3_f32 v25, v25, s35, v84
	v_mov_b32_e32 v26, 0
	v_cvt_scalef32_pk_fp4_f32 v26, v24, v25, 1.0
	v_add_f32_e32 v24, v22, v22
	v_add_f32_e32 v25, v23, v23
	v_med3_f32 v24, v24, s35, v84
	v_med3_f32 v25, v25, s35, v84
	v_cvt_scalef32_pk_fp4_f32 v26, v24, v25, 1.0 op_sel:[0,0,1,0]
	v_add_f32_e32 v24, v16, v16
	v_add_f32_e32 v25, v17, v17
	v_med3_f32 v24, v24, s35, v84
	v_med3_f32 v25, v25, s35, v84
	v_cvt_scalef32_pk_fp4_f32 v26, v24, v25, 1.0 op_sel:[0,0,0,1]
	v_add_f32_e32 v24, v18, v18
	v_add_f32_e32 v25, v19, v19
	v_med3_f32 v24, v24, s35, v84
	v_med3_f32 v25, v25, s35, v84
	v_cvt_scalef32_pk_fp4_f32 v26, v24, v25, 1.0 op_sel:[0,0,1,1]
	v_lshrrev_b64 v[24:25], 1, v[28:29]
	v_lshl_add_u64 v[24:25], s[52:53], 0, v[24:25]
	global_store_dword v[24:25], v26, off
	ds_write_b128 v80, v[20:23]
	ds_write_b128 v80, v[16:19] offset:16
	v_cvt_pk_bf16_f32 v16, v12, v13
	v_cvt_pk_bf16_f32 v17, v14, v15
	v_cvt_pk_bf16_f32 v18, v8, v9
	v_cvt_pk_bf16_f32 v19, v10, v11
	global_store_dwordx4 v[72:73], v[16:19], off
	v_lshl_add_u64 v[20:21], v[90:91], 0, s[70:71]
	v_mov_b32_e32 v33, v32
	v_add_f32_e32 v16, v12, v12
	v_add_f32_e32 v17, v13, v13
	v_med3_f32 v16, v16, s35, v84
	v_med3_f32 v17, v17, s35, v84
	v_mov_b32_e32 v18, 0
	v_cvt_scalef32_pk_fp4_f32 v18, v16, v17, 1.0
	v_add_f32_e32 v16, v14, v14
	v_add_f32_e32 v17, v15, v15
	v_med3_f32 v16, v16, s35, v84
	v_med3_f32 v17, v17, s35, v84
	v_cvt_scalef32_pk_fp4_f32 v18, v16, v17, 1.0 op_sel:[0,0,1,0]
	v_add_f32_e32 v16, v8, v8
	v_add_f32_e32 v17, v9, v9
	v_med3_f32 v16, v16, s35, v84
	v_med3_f32 v17, v17, s35, v84
	v_cvt_scalef32_pk_fp4_f32 v18, v16, v17, 1.0 op_sel:[0,0,0,1]
	v_add_f32_e32 v16, v10, v10
	v_add_f32_e32 v17, v11, v11
	v_med3_f32 v16, v16, s35, v84
	v_med3_f32 v17, v17, s35, v84
	v_cvt_scalef32_pk_fp4_f32 v18, v16, v17, 1.0 op_sel:[0,0,1,1]
	v_lshrrev_b64 v[16:17], 1, v[20:21]
	v_lshl_add_u64 v[16:17], s[52:53], 0, v[16:17]
	global_store_dword v[16:17], v18, off
	ds_write_b128 v81, v[12:15]
	ds_write_b128 v81, v[8:11] offset:16
	v_cvt_pk_bf16_f32 v8, v4, v5
	v_cvt_pk_bf16_f32 v9, v6, v7
	v_cvt_pk_bf16_f32 v10, v0, v1
	v_cvt_pk_bf16_f32 v11, v2, v3
	global_store_dwordx4 v[72:73], v[8:11], off offset:1024
	v_lshl_add_u64 v[12:13], v[90:91], 0, s[76:77]
	s_add_u32 s16, s16, s58
	v_add_f32_e32 v8, v4, v4
	v_add_f32_e32 v9, v5, v5
	v_med3_f32 v8, v8, s35, v84
	v_med3_f32 v9, v9, s35, v84
	v_mov_b32_e32 v10, 0
	v_cvt_scalef32_pk_fp4_f32 v10, v8, v9, 1.0
	v_add_f32_e32 v8, v6, v6
	v_add_f32_e32 v9, v7, v7
	v_med3_f32 v8, v8, s35, v84
	v_med3_f32 v9, v9, s35, v84
	v_cvt_scalef32_pk_fp4_f32 v10, v8, v9, 1.0 op_sel:[0,0,1,0]
	v_add_f32_e32 v8, v0, v0
	v_add_f32_e32 v9, v1, v1
	v_med3_f32 v8, v8, s35, v84
	v_med3_f32 v9, v9, s35, v84
	v_cvt_scalef32_pk_fp4_f32 v10, v8, v9, 1.0 op_sel:[0,0,0,1]
	v_add_f32_e32 v8, v2, v2
	v_add_f32_e32 v9, v3, v3
	v_med3_f32 v8, v8, s35, v84
	v_med3_f32 v9, v9, s35, v84
	v_cvt_scalef32_pk_fp4_f32 v10, v8, v9, 1.0 op_sel:[0,0,1,1]
	v_lshrrev_b64 v[8:9], 1, v[12:13]
	v_lshl_add_u64 v[8:9], s[52:53], 0, v[8:9]
	global_store_dword v[8:9], v10, off
	ds_write_b128 v82, v[4:7]
	ds_write_b128 v82, v[0:3] offset:16
	s_waitcnt lgkmcnt(0)
; #define LAS __attribute__((address_space(3)))
; #define LDS_WAIT() asm volatile("s_waitcnt lgkmcnt(0)" ::: "memory")
; #define XLOAD(blk_) do { const size_t e0_ = (blk_) * 2048; const float* s0_ = (e0_ < (size_t)SEQ * DM) ? F.xp + e0_ : F.xs + (e0_ - (size_t)SEQ * DM); \
;     _Pragma("unroll") for (int i = 0; i < 4; ++i) { const float* s_ = s0_ + (i * 64 + plane) * 8; la[i] = *(const f32x4*)s_; lb[i] = *(const f32x4*)(s_ + 4); } } while (0)
;     __device__ __forceinline__ unsigned a(const pg8::Unit& u) const { return (unsigned)u.pm * (256u * K * 2u); }
;     __device__ __forceinline__ unsigned a(const pg8::Unit& u) const { return (unsigned)u.pm * (256u * K * 2u); }
;     __device__ __forceinline__ unsigned a(const pg8::Unit& u) const { return (unsigned)u.pm * (256u * K * 2u); }
;     __device__ __forceinline__ unsigned a(const pg8::Unit& u) const { return (unsigned)u.pm * (256u * K * 2u); }
;     __device__ __forceinline__ unsigned a(const pg8::Unit& u) const { return (unsigned)u.pm * (256u * K * 2u); }
; __device__ __forceinline__ void p0_prologue(const Frame& F) {
;     ...
;         for (; blk < NB; blk += NGW) {
;             const size_t e0 = blk * 2048;
;             f32x4 a[4], b[4];
; #pragma unroll
;             for (int i = 0; i < 4; ++i) { a[i] = la[i]; b[i] = lb[i]; }
;             if (blk + NGW < NB) XLOAD(blk + NGW);
;     ...
;             LDS_WAIT(); asm volatile("" ::: "memory");
;             float v[32];
; #pragma unroll
;             for (int j = 0; j < 8; ++j) { const f32x4 t = *(const LAS f32x4*)(scr + plane * 36 + j * 4); v[4 * j] = t[0]; v[4 * j + 1] = t[1]; v[4 * j + 2] = t[2]; v[4 * j + 3] = t[3]; }
;             const size_t eg = e0 + (size_t)plane * 32;
;             store_fp6_group(F.XB8 + (eg >> 7) * 128 + ((eg >> 5) & 3) * 16, v, X6_SCALE);
;             LDS_WAIT(); asm volatile("" ::: "memory");
	ds_read_b128 v[0:3], v83
	ds_read_b128 v[4:7], v83 offset:16
	ds_read_b128 v[8:11], v83 offset:32
	ds_read_b128 v[12:15], v83 offset:48
	ds_read_b128 v[16:19], v83 offset:64
	ds_read_b128 v[20:23], v83 offset:80
	ds_read_b128 v[24:27], v83 offset:96
	ds_read_b128 v[28:31], v83 offset:112
	s_waitcnt lgkmcnt(7)
	v_add_f32_e32 v0, v0, v0
	s_waitcnt lgkmcnt(3)
	v_add_f32_e32 v16, v16, v16
	v_add_f32_e32 v1, v1, v1
	v_add_f32_e32 v17, v17, v17
	v_add_f32_e32 v2, v2, v2
	v_add_f32_e32 v18, v18, v18
	v_add_f32_e32 v3, v3, v3
	v_add_f32_e32 v19, v19, v19
	v_add_f32_e32 v4, v4, v4
	s_waitcnt lgkmcnt(2)
	v_add_f32_e32 v20, v20, v20
	v_add_f32_e32 v5, v5, v5
	v_add_f32_e32 v21, v21, v21
	v_add_f32_e32 v6, v6, v6
	v_add_f32_e32 v22, v22, v22
	v_add_f32_e32 v7, v7, v7
	v_add_f32_e32 v23, v23, v23
	v_add_f32_e32 v8, v8, v8
	s_waitcnt lgkmcnt(1)
	v_add_f32_e32 v24, v24, v24
	v_add_f32_e32 v9, v9, v9
	v_add_f32_e32 v25, v25, v25
	v_add_f32_e32 v10, v10, v10
	v_add_f32_e32 v26, v26, v26
	v_add_f32_e32 v11, v11, v11
	v_add_f32_e32 v27, v27, v27
	v_add_f32_e32 v12, v12, v12
	s_waitcnt lgkmcnt(0)
	v_add_f32_e32 v28, v28, v28
	v_add_f32_e32 v13, v13, v13
	v_add_f32_e32 v29, v29, v29
	v_add_f32_e32 v14, v14, v14
	v_add_f32_e32 v30, v30, v30
	v_add_f32_e32 v15, v15, v15
	v_add_f32_e32 v31, v31, v31
	v_med3_f32 v0, v0, s3, v85
	v_med3_f32 v16, v16, s3, v85
	v_med3_f32 v1, v1, s3, v85
	v_med3_f32 v17, v17, s3, v85
	v_med3_f32 v2, v2, s3, v85
	v_med3_f32 v18, v18, s3, v85
	v_med3_f32 v3, v3, s3, v85
	v_med3_f32 v19, v19, s3, v85
	v_med3_f32 v4, v4, s3, v85
	v_med3_f32 v20, v20, s3, v85
	v_med3_f32 v5, v5, s3, v85
	v_med3_f32 v21, v21, s3, v85
	v_med3_f32 v6, v6, s3, v85
	v_med3_f32 v22, v22, s3, v85
	v_med3_f32 v7, v7, s3, v85
	v_med3_f32 v23, v23, s3, v85
	v_med3_f32 v8, v8, s3, v85
	v_med3_f32 v24, v24, s3, v85
	v_med3_f32 v9, v9, s3, v85
	v_med3_f32 v25, v25, s3, v85
	v_med3_f32 v10, v10, s3, v85
	v_med3_f32 v26, v26, s3, v85
	v_med3_f32 v11, v11, s3, v85
	v_med3_f32 v27, v27, s3, v85
	v_med3_f32 v12, v12, s3, v85
	v_med3_f32 v28, v28, s3, v85
	v_med3_f32 v13, v13, s3, v85
	v_med3_f32 v29, v29, s3, v85
	v_med3_f32 v14, v14, s3, v85
	v_med3_f32 v30, v30, s3, v85
	v_med3_f32 v15, v15, s3, v85
	v_med3_f32 v31, v31, s3, v85
	v_cvt_scalef32_2xpk16_fp6_f32 v[0:5], v[0:15], v[16:31], 1.0
	v_add_co_u32_e32 v6, vcc, s72, v86
	v_mov_b32_e32 v30, v4
	s_nop 0
	v_addc_co_u32_e32 v7, vcc, 0, v87, vcc
	v_mov_b32_e32 v31, v5
	v_mbcnt_lo_u32_b32 v8, -1, 0
	v_mbcnt_hi_u32_b32 v8, -1, v8
	v_and_b32_e32 v8, 3, v8
	v_mov_b32_e32 v9, s50
	v_bfe_u32 v15, v9, 4, 1
	v_bfe_u32 v14, v9, 7, 1
	v_bfe_u32 v12, v9, 1, 1
	v_and_b32_e32 v12, v12, v14
	v_mul_u32_u24_e32 v12, 0xfc0, v12
	v_bfe_u32 v9, v9, 3, 2
	v_and_b32_e32 v13, 1, v9
	v_sub_u32_e32 v9, 0, v9
	v_and_b32_e32 v9, 3, v9
	v_xor_b32_e32 v9, v8, v9
	v_sub_u32_e32 v9, v9, v8
	v_lshlrev_b32_e32 v10, 4, v9
	v_sub_u32_e32 v10, v10, v12
	v_ashrrev_i32_e32 v11, 31, v10
	v_lshl_add_u64 v[10:11], v[6:7], 0, v[10:11]
	s_barrier
	global_store_dwordx4 v[10:11], v[0:3], off
	v_xor_b32_e32 v13, v14, v13
	v_lshlrev_b32_e32 v13, 5, v13
	v_lshlrev_b32_e32 v14, 18, v14
	v_sub_u32_e32 v13, v13, v14
	v_lshrrev_b32_e32 v14, 1, v8
	v_xor_b32_e32 v14, v14, v15
	v_lshl_add_u32 v13, v14, 4, v13
	v_and_b32_e32 v14, 1, v8
	v_lshl_add_u32 v13, v14, 3, v13
	v_lshlrev_b32_e32 v14, 4, v8
	v_sub_u32_e32 v12, v13, v14
	v_ashrrev_i32_e32 v13, 31, v12
	v_lshl_add_u64 v[12:13], v[6:7], 0, v[12:13]
	global_store_dwordx2 v[12:13], v[30:31], off offset:64
	s_waitcnt lgkmcnt(0)
	s_waitcnt vmcnt(17)
	v_mov_b64_e32 v[24:25], v[34:35]
	s_waitcnt vmcnt(15)
	v_mov_b64_e32 v[16:17], v[42:43]
	s_waitcnt vmcnt(12)
	v_mov_b64_e32 v[8:9], v[50:51]
	s_waitcnt vmcnt(10)
	v_mov_b64_e32 v[0:1], v[58:59]
	v_mov_b64_e32 v[28:29], v[38:39]
	v_mov_b64_e32 v[20:21], v[46:47]
	v_mov_b64_e32 v[12:13], v[54:55]
	v_mov_b64_e32 v[4:5], v[62:63]
	s_addc_u32 s17, s17, s59
	v_lshl_add_u64 v[70:71], v[70:71], 0, s[62:63]
	v_lshl_add_u64 v[78:79], v[78:79], 0, s[62:63]
	v_lshl_add_u64 v[72:73], v[72:73], 0, s[66:67]
	s_andn2_b64 vcc, exec, s[0:1]
	v_mov_b64_e32 v[26:27], v[36:37]
	v_mov_b64_e32 v[18:19], v[44:45]
	v_mov_b64_e32 v[10:11], v[52:53]
	v_mov_b64_e32 v[2:3], v[60:61]
	v_mov_b64_e32 v[30:31], v[40:41]
	v_mov_b64_e32 v[22:23], v[48:49]
	v_mov_b64_e32 v[14:15], v[56:57]
	v_mov_b64_e32 v[6:7], v[64:65]
	s_cbranch_vccz .LBB0_54

; __device__ __forceinline__ void p6_final_ln(const Frame& F) {
;     ...
;     for (int m = gw; m < M; m += NGW) {
;         const float* xr = (m < SEQ) ? F.xp + (size_t)m * DM : F.xs + (size_t)(m - SEQ) * DM;
;         const bf16_t* orow = F.OUTB + (size_t)m * DM;
;         f32x4 z[16]; float s = 0.f;
; #pragma unroll
;         for (int j = 0; j < 8; ++j) { const int col = j * 512 + lane * 8;
;             const f32x4 xa = *(const f32x4*)(xr + col), xb = *(const f32x4*)(xr + col + 4); const u32x4 o = *(const u32x4*)(orow + col);
;             z[2 * j]     = xa * DN_ALPHA + (f32x4){bflo(o.x), bfhi(o.x), bflo(o.y), bfhi(o.y)};
;             z[2 * j + 1] = xb * DN_ALPHA + (f32x4){bflo(o.z), bfhi(o.z), bflo(o.w), bfhi(o.w)};
;             s += (z[2 * j][0] + z[2 * j][1]) + (z[2 * j][2] + z[2 * j][3]) + (z[2 * j + 1][0] + z[2 * j + 1][1]) + (z[2 * j + 1][2] + z[2 * j + 1][3]); }
.LBB0_575:
	s_barrier
	s_lshl_b64 s[18:19], s[12:13], 13
	s_add_u32 s18, s26, s18
	s_addc_u32 s19, s27, s19
	v_lshlrev_b32_e32 v70, 1, v4
	global_load_dwordx4 v[42:45], v70, s[18:19]
	global_load_dwordx4 v[46:49], v70, s[18:19] offset:1024
	global_load_dwordx4 v[50:53], v70, s[18:19] offset:2048
	v_lshlrev_b32_e32 v109, 2, v4
	global_load_dwordx4 v[54:57], v109, s[16:17]
	global_load_dwordx4 v[58:61], v109, s[16:17] offset:16
	global_load_dwordx4 v[62:65], v109, s[16:17] offset:2048
	global_load_dwordx4 v[66:69], v109, s[16:17] offset:2064
	global_load_dwordx4 v[74:77], v104, s[16:17]
	global_load_dwordx4 v[78:81], v104, s[16:17] offset:16
	global_load_dwordx4 v[0:3], v105, s[16:17] offset:16
	global_load_dwordx4 v[82:85], v105, s[16:17]
	v_lshlrev_b32_e32 v107, 2, v6
	v_lshlrev_b32_e32 v71, 1, v6
	v_lshlrev_b32_e32 v108, 2, v8
	v_lshlrev_b32_e32 v72, 1, v8
	global_load_dwordx4 v[86:89], v107, s[16:17] offset:16
	global_load_dwordx4 v[94:97], v107, s[16:17]
	global_load_dwordx4 v[112:115], v108, s[16:17] offset:16
	global_load_dwordx4 v[116:119], v108, s[16:17]
	global_load_dwordx4 v[98:101], v70, s[18:19] offset:3072
	global_load_dwordx4 v[120:123], v71, s[18:19]
	global_load_dwordx4 v[124:127], v72, s[18:19]
	s_lshl_b64 s[12:13], s[12:13], 14
	s_add_u32 s12, s38, s12
	s_addc_u32 s13, s39, s13
	s_add_u32 s0, s0, s2
	s_addc_u32 s1, s1, s3
	s_add_u32 s6, s6, s8
	s_addc_u32 s7, s7, s9
	s_cmpk_lt_i32 s0, 0x6000
	s_waitcnt vmcnt(17)
	v_lshlrev_b32_e32 v70, 16, v42
	v_and_b32_e32 v71, 0xffff0000, v42
	v_lshlrev_b32_e32 v42, 16, v43
	v_and_b32_e32 v43, 0xffff0000, v43
	v_lshlrev_b32_e32 v72, 16, v44
	v_and_b32_e32 v73, 0xffff0000, v44
	v_lshlrev_b32_e32 v44, 16, v45
	v_and_b32_e32 v45, 0xffff0000, v45
	s_waitcnt vmcnt(16)
	v_lshlrev_b32_e32 v110, 16, v46
	v_and_b32_e32 v111, 0xffff0000, v46
	v_lshlrev_b32_e32 v46, 16, v47
	v_and_b32_e32 v47, 0xffff0000, v47
	v_lshlrev_b32_e32 v128, 16, v48
	v_and_b32_e32 v129, 0xffff0000, v48
	v_lshlrev_b32_e32 v48, 16, v49
	v_and_b32_e32 v49, 0xffff0000, v49
	s_waitcnt vmcnt(14)
	v_pk_fma_f32 v[90:91], v[56:57], s[10:11], v[42:43] op_sel_hi:[1,0,1]
	v_pk_fma_f32 v[92:93], v[54:55], s[10:11], v[70:71] op_sel_hi:[1,0,1]
	s_waitcnt vmcnt(13)
	v_pk_fma_f32 v[70:71], v[60:61], s[10:11], v[44:45] op_sel_hi:[1,0,1]
	v_pk_fma_f32 v[72:73], v[58:59], s[10:11], v[72:73] op_sel_hi:[1,0,1]
	s_waitcnt vmcnt(12)
	v_pk_fma_f32 v[60:61], v[64:65], s[10:11], v[46:47] op_sel_hi:[1,0,1]
	v_pk_fma_f32 v[58:59], v[62:63], s[10:11], v[110:111] op_sel_hi:[1,0,1]
	s_waitcnt vmcnt(11)
	v_pk_fma_f32 v[56:57], v[68:69], s[10:11], v[48:49] op_sel_hi:[1,0,1]
	v_pk_fma_f32 v[54:55], v[66:67], s[10:11], v[128:129] op_sel_hi:[1,0,1]
	v_mov_b32_e32 v46, v92
	v_mov_b32_e32 v47, v58
	v_mov_b32_e32 v48, v93
	v_mov_b32_e32 v49, v59
	v_mov_b32_e32 v62, v90
	v_mov_b32_e32 v63, v60
	v_mov_b32_e32 v64, v91
	v_mov_b32_e32 v65, v61
	v_lshlrev_b32_e32 v130, 16, v50
	v_and_b32_e32 v131, 0xffff0000, v50
	v_lshlrev_b32_e32 v50, 16, v51
	v_and_b32_e32 v51, 0xffff0000, v51
	v_mov_b32_e32 v66, v72
	v_mov_b32_e32 v67, v54
	v_mov_b32_e32 v68, v73
	v_mov_b32_e32 v69, v55
	v_pk_add_f32 v[46:47], v[46:47], v[48:49]
	v_pk_add_f32 v[48:49], v[62:63], v[64:65]
	v_lshlrev_b32_e32 v132, 16, v52
	v_and_b32_e32 v133, 0xffff0000, v52
	v_lshlrev_b32_e32 v134, 16, v53
	v_and_b32_e32 v135, 0xffff0000, v53
	s_waitcnt vmcnt(10)
	v_pk_fma_f32 v[52:53], v[76:77], s[10:11], v[50:51] op_sel_hi:[1,0,1]
	v_pk_fma_f32 v[50:51], v[74:75], s[10:11], v[130:131] op_sel_hi:[1,0,1]
	v_mov_b32_e32 v74, v70
	v_mov_b32_e32 v75, v56
	v_mov_b32_e32 v76, v71
	v_mov_b32_e32 v77, v57
	v_pk_add_f32 v[62:63], v[66:67], v[68:69]
	v_pk_add_f32 v[46:47], v[46:47], v[48:49]
	v_pk_add_f32 v[64:65], v[74:75], v[76:77]
	v_pk_add_f32 v[46:47], v[62:63], v[46:47]
	s_waitcnt vmcnt(9)
	v_pk_fma_f32 v[44:45], v[80:81], s[10:11], v[134:135] op_sel_hi:[1,0,1]
	v_pk_fma_f32 v[42:43], v[78:79], s[10:11], v[132:133] op_sel_hi:[1,0,1]
	v_pk_mov_b32 v[78:79], v[50:51], v[52:53] op_sel:[1,0]
	v_mov_b32_e32 v80, v50
	v_mov_b32_e32 v81, v53
	v_pk_add_f32 v[46:47], v[64:65], v[46:47]
	v_pk_add_f32 v[66:67], v[78:79], v[80:81]
	v_add_f32_e32 v46, 0, v46
	v_mov_b32_e32 v48, v44
	v_mov_b32_e32 v49, v42
	v_mov_b32_e32 v62, v45
	v_mov_b32_e32 v63, v43
	v_add_f32_e32 v76, v46, v47
	v_pk_add_f32 v[46:47], v[66:67], v[66:67] op_sel:[0,1] op_sel_hi:[1,0]
	v_pk_add_f32 v[62:63], v[48:49], v[62:63]
	v_lshlrev_b32_e32 v111, 2, v10
	v_pk_add_f32 v[64:65], v[62:63], v[46:47] op_sel:[1,0] op_sel_hi:[0,1]
	v_lshlrev_b32_e32 v46, 1, v10
	global_load_dwordx4 v[46:49], v46, s[18:19]
	v_pk_add_f32 v[78:79], v[62:63], v[64:65]
	global_load_dwordx4 v[62:65], v111, s[16:17] offset:16
	global_load_dwordx4 v[66:69], v111, s[16:17]
	v_lshlrev_b32_e32 v77, 1, v12
	global_load_dwordx4 v[128:131], v77, s[18:19]
	v_lshlrev_b32_e32 v110, 2, v12
	global_load_dwordx4 v[132:135], v110, s[16:17] offset:16
	global_load_dwordx4 v[136:139], v110, s[16:17]
	s_waitcnt vmcnt(8)
	v_lshlrev_b32_e32 v74, 16, v98
	v_and_b32_e32 v75, 0xffff0000, v98
	v_lshlrev_b32_e32 v80, 16, v99
	v_and_b32_e32 v81, 0xffff0000, v99
	v_pk_fma_f32 v[80:81], v[84:85], s[10:11], v[80:81] op_sel_hi:[1,0,1]
	v_pk_fma_f32 v[74:75], v[82:83], s[10:11], v[74:75] op_sel_hi:[1,0,1]
	v_lshlrev_b32_e32 v82, 16, v100
	v_and_b32_e32 v83, 0xffff0000, v100
	v_lshlrev_b32_e32 v84, 16, v101
	v_and_b32_e32 v85, 0xffff0000, v101
	v_pk_fma_f32 v[100:101], v[2:3], s[10:11], v[84:85] op_sel_hi:[1,0,1]
	v_pk_fma_f32 v[98:99], v[0:1], s[10:11], v[82:83] op_sel_hi:[1,0,1]
	s_waitcnt vmcnt(7)
; __device__ __forceinline__ float wave_sum(float v) {
; #pragma unroll
;     for (int o = 1; o < 64; o <<= 1) v += __shfl_xor(v, o);
;     return v;
; __device__ __forceinline__ void p6_final_ln(const Frame& F) {
;     ...
;         for (int j = 0; j < 8; ++j) { const int col = j * 512 + lane * 8;
;             const f32x4 xa = *(const f32x4*)(xr + col), xb = *(const f32x4*)(xr + col + 4); const u32x4 o = *(const u32x4*)(orow + col);
;             z[2 * j]     = xa * DN_ALPHA + (f32x4){bflo(o.x), bfhi(o.x), bflo(o.y), bfhi(o.y)};
;             z[2 * j + 1] = xb * DN_ALPHA + (f32x4){bflo(o.z), bfhi(o.z), bflo(o.w), bfhi(o.w)};
;             s += (z[2 * j][0] + z[2 * j][1]) + (z[2 * j][2] + z[2 * j][3]) + (z[2 * j + 1][0] + z[2 * j + 1][1]) + (z[2 * j + 1][2] + z[2 * j + 1][3]); }
;         const float mean = wave_sum(s) * (1.f / DM); float q = 0.f;
	v_lshlrev_b32_e32 v82, 16, v120
	v_and_b32_e32 v83, 0xffff0000, v120
	v_lshlrev_b32_e32 v84, 16, v121
	v_and_b32_e32 v85, 0xffff0000, v121
	v_pk_fma_f32 v[96:97], v[96:97], s[10:11], v[84:85] op_sel_hi:[1,0,1]
	v_pk_fma_f32 v[94:95], v[94:95], s[10:11], v[82:83] op_sel_hi:[1,0,1]
	v_lshlrev_b32_e32 v82, 16, v122
	v_and_b32_e32 v83, 0xffff0000, v122
	v_lshlrev_b32_e32 v84, 16, v123
	v_and_b32_e32 v85, 0xffff0000, v123
	v_add_f32_e32 v0, v74, v75
	v_add_f32_e32 v2, v80, v81
	v_pk_fma_f32 v[84:85], v[88:89], s[10:11], v[84:85] op_sel_hi:[1,0,1]
	v_pk_fma_f32 v[82:83], v[86:87], s[10:11], v[82:83] op_sel_hi:[1,0,1]
	v_mov_b32_e32 v86, v98
	v_mov_b32_e32 v87, v94
	v_mov_b32_e32 v88, v99
	v_mov_b32_e32 v89, v95
	v_mov_b32_e32 v1, v96
	v_mov_b32_e32 v3, v97
	v_pk_add_f32 v[86:87], v[86:87], v[88:89]
	v_pk_add_f32 v[0:1], v[0:1], v[2:3]
	v_mov_b32_e32 v2, v100
	v_pk_add_f32 v[0:1], v[86:87], v[0:1]
	v_mov_b32_e32 v3, v82
	v_mov_b32_e32 v86, v101
	v_mov_b32_e32 v87, v83
	v_pk_add_f32 v[2:3], v[2:3], v[86:87]
	v_mov_b32_e32 v77, v84
	v_mov_b32_e32 v79, v85
	v_pk_add_f32 v[0:1], v[2:3], v[0:1]
	v_pk_add_f32 v[2:3], v[76:77], v[78:79]
	s_nop 0
	v_pk_add_f32 v[0:1], v[2:3], v[0:1]
	s_waitcnt vmcnt(6)
	v_lshlrev_b32_e32 v2, 16, v125
	v_pk_add_f32 v[120:121], v[0:1], v[0:1] op_sel:[0,1] op_sel_hi:[1,0]
	v_lshlrev_b32_e32 v0, 16, v124
	v_and_b32_e32 v1, 0xffff0000, v124
	v_and_b32_e32 v3, 0xffff0000, v125
	v_pk_fma_f32 v[88:89], v[118:119], s[10:11], v[2:3] op_sel_hi:[1,0,1]
	v_pk_fma_f32 v[86:87], v[116:117], s[10:11], v[0:1] op_sel_hi:[1,0,1]
	v_lshlrev_b32_e32 v0, 16, v126
	v_and_b32_e32 v1, 0xffff0000, v126
	v_lshlrev_b32_e32 v2, 16, v127
	v_and_b32_e32 v3, 0xffff0000, v127
	v_pk_fma_f32 v[78:79], v[114:115], s[10:11], v[2:3] op_sel_hi:[1,0,1]
	v_pk_fma_f32 v[76:77], v[112:113], s[10:11], v[0:1] op_sel_hi:[1,0,1]
	v_pk_mov_b32 v[0:1], v[86:87], v[88:89] op_sel:[1,0]
	v_mov_b32_e32 v2, v86
	v_mov_b32_e32 v3, v89
	v_pk_add_f32 v[0:1], v[0:1], v[2:3]
	v_mov_b32_e32 v2, v78
	v_mov_b32_e32 v3, v76
	v_mov_b32_e32 v112, v79
	v_mov_b32_e32 v113, v77
	v_pk_add_f32 v[0:1], v[0:1], v[0:1] op_sel:[0,1] op_sel_hi:[1,0]
	v_pk_add_f32 v[2:3], v[2:3], v[112:113]
	s_nop 0
	v_pk_add_f32 v[0:1], v[2:3], v[0:1] op_sel:[1,0] op_sel_hi:[0,1]
	v_pk_add_f32 v[112:113], v[2:3], v[0:1]
	s_waitcnt vmcnt(5)
	v_lshlrev_b32_e32 v0, 16, v46
	v_and_b32_e32 v1, 0xffff0000, v46
	v_lshlrev_b32_e32 v2, 16, v47
	v_and_b32_e32 v3, 0xffff0000, v47
	s_waitcnt vmcnt(3)
	v_pk_fma_f32 v[68:69], v[68:69], s[10:11], v[2:3] op_sel_hi:[1,0,1]
	v_pk_fma_f32 v[66:67], v[66:67], s[10:11], v[0:1] op_sel_hi:[1,0,1]
	v_lshlrev_b32_e32 v0, 16, v48
	v_and_b32_e32 v1, 0xffff0000, v48
	v_lshlrev_b32_e32 v2, 16, v49
	v_and_b32_e32 v3, 0xffff0000, v49
	v_pk_fma_f32 v[64:65], v[64:65], s[10:11], v[2:3] op_sel_hi:[1,0,1]
	v_pk_fma_f32 v[62:63], v[62:63], s[10:11], v[0:1] op_sel_hi:[1,0,1]
	s_waitcnt vmcnt(2)
	v_lshlrev_b32_e32 v2, 16, v128
	v_and_b32_e32 v3, 0xffff0000, v128
	v_lshlrev_b32_e32 v0, 16, v129
	v_and_b32_e32 v1, 0xffff0000, v129
	s_waitcnt vmcnt(0)
	v_pk_fma_f32 v[0:1], v[138:139], s[10:11], v[0:1] op_sel_hi:[1,0,1]
	v_pk_fma_f32 v[2:3], v[136:137], s[10:11], v[2:3] op_sel_hi:[1,0,1]
	v_add_f32_e32 v114, v66, v67
	v_add_f32_e32 v116, v68, v69
	v_lshlrev_b32_e32 v48, 16, v130
	v_and_b32_e32 v49, 0xffff0000, v130
	v_mov_b32_e32 v118, v62
	v_mov_b32_e32 v119, v2
	v_mov_b32_e32 v122, v63
	v_mov_b32_e32 v123, v3
	v_mov_b32_e32 v115, v0
	v_mov_b32_e32 v117, v1
	v_lshlrev_b32_e32 v46, 16, v131
	v_and_b32_e32 v47, 0xffff0000, v131
	v_pk_fma_f32 v[48:49], v[132:133], s[10:11], v[48:49] op_sel_hi:[1,0,1]
	v_pk_add_f32 v[118:119], v[118:119], v[122:123]
	v_pk_add_f32 v[114:115], v[114:115], v[116:117]
	v_pk_fma_f32 v[46:47], v[134:135], s[10:11], v[46:47] op_sel_hi:[1,0,1]
	v_pk_add_f32 v[114:115], v[118:119], v[114:115]
	v_mov_b32_e32 v116, v64
	v_mov_b32_e32 v117, v48
	v_mov_b32_e32 v118, v65
	v_mov_b32_e32 v119, v49
	v_pk_add_f32 v[116:117], v[116:117], v[118:119]
	v_mov_b32_e32 v121, v46
	v_mov_b32_e32 v113, v47
	v_pk_add_f32 v[114:115], v[116:117], v[114:115]
	v_pk_add_f32 v[112:113], v[120:121], v[112:113]
	s_nop 0
	v_pk_add_f32 v[112:113], v[112:113], v[114:115]
	s_nop 0
	v_add_f32_e32 v102, v112, v113
	ds_bpermute_b32 v112, v5, v102
	s_waitcnt lgkmcnt(0)
	v_add_f32_e32 v102, v102, v112
	ds_bpermute_b32 v112, v7, v102
	s_waitcnt lgkmcnt(0)
	v_add_f32_e32 v102, v102, v112
	ds_bpermute_b32 v112, v9, v102
	s_waitcnt lgkmcnt(0)
	v_add_f32_e32 v102, v102, v112
	ds_bpermute_b32 v112, v11, v102
	s_waitcnt lgkmcnt(0)
	v_add_f32_e32 v102, v102, v112
	ds_bpermute_b32 v112, v13, v102
	s_waitcnt lgkmcnt(0)
	v_add_f32_e32 v102, v102, v112
	ds_bpermute_b32 v112, v103, v102
	s_waitcnt lgkmcnt(0)
; __device__ __forceinline__ void p6_final_ln(const Frame& F) {
;     ...
;         const float mean = wave_sum(s) * (1.f / DM); float q = 0.f;
; #pragma unroll
;         for (int j = 0; j < 16; ++j) { const f32x4 d = z[j] - mean; z[j] = d; q += (d[0] * d[0] + d[1] * d[1]) + (d[2] * d[2] + d[3] * d[3]); }
;         const float rstd = __builtin_amdgcn_rsqf(wave_sum(q) * (1.f / DM) + LN_EPS);
;         float* yr = F.out + (size_t)m * DM;
; #pragma unroll
;         for (int j = 0; j < 8; ++j) { const int col = j * 512 + lane * 8;
;             const f32x4 ga = *(const f32x4*)(F.ln_g + col), gb = *(const f32x4*)(F.ln_g + col + 4), ba = *(const f32x4*)(F.ln_b + col), bb = *(const f32x4*)(F.ln_b + col + 4);
	v_add_f32_e32 v136, v102, v112
	v_fmamk_f32 v93, v136, 0xb9800000, v93
	v_fmac_f32_e32 v92, 0xb9800000, v136
	v_fmamk_f32 v91, v136, 0xb9800000, v91
	v_fmac_f32_e32 v90, 0xb9800000, v136
	v_pk_mul_f32 v[112:113], v[90:91], v[90:91]
	v_pk_mul_f32 v[114:115], v[92:93], v[92:93]
	v_fmamk_f32 v73, v136, 0xb9800000, v73
	v_pk_mov_b32 v[116:117], v[114:115], v[112:113] op_sel:[1,0]
	v_mov_b32_e32 v115, v113
	v_fmac_f32_e32 v72, 0xb9800000, v136
	v_fmamk_f32 v71, v136, 0xb9800000, v71
	v_fmac_f32_e32 v70, 0xb9800000, v136
	v_pk_add_f32 v[112:113], v[116:117], v[114:115]
	v_pk_mul_f32 v[114:115], v[70:71], v[70:71]
	v_pk_mul_f32 v[116:117], v[72:73], v[72:73]
	v_fmac_f32_e32 v58, 0xb9800000, v136
	v_pk_mov_b32 v[118:119], v[116:117], v[114:115] op_sel:[1,0]
	v_mov_b32_e32 v117, v115
	v_fmamk_f32 v59, v136, 0xb9800000, v59
	v_fmac_f32_e32 v60, 0xb9800000, v136
	v_mul_f32_e32 v102, v58, v58
	v_pk_add_f32 v[114:115], v[118:119], v[116:117]
	v_fmamk_f32 v61, v136, 0xb9800000, v61
	v_pk_fma_f32 v[116:117], v[58:59], v[58:59], v[102:103] op_sel_hi:[1,1,0]
	v_mul_f32_e32 v102, v60, v60
	v_pk_add_f32 v[112:113], v[112:113], v[112:113] op_sel_hi:[0,1]
	v_pk_add_f32 v[114:115], v[114:115], v[114:115] op_sel_hi:[0,1]
	v_pk_fma_f32 v[118:119], v[60:61], v[60:61], v[102:103] op_sel_hi:[1,1,0]
	v_fmamk_f32 v57, v136, 0xb9800000, v57
	v_fmac_f32_e32 v56, 0xb9800000, v136
	v_fmamk_f32 v55, v136, 0xb9800000, v55
	v_fmac_f32_e32 v54, 0xb9800000, v136
	v_mul_f32_e32 v116, v54, v54
	v_mul_f32_e32 v118, v55, v55
	v_mul_f32_e32 v112, v56, v56
	v_mul_f32_e32 v114, v57, v57
	v_pk_add_f32 v[116:117], v[116:117], v[118:119]
	v_pk_add_f32 v[112:113], v[112:113], v[114:115]
	v_fmamk_f32 v51, v136, 0xb9800000, v51
	v_fmac_f32_e32 v50, 0xb9800000, v136
	v_fmamk_f32 v53, v136, 0xb9800000, v53
	v_fmac_f32_e32 v52, 0xb9800000, v136
	v_pk_add_f32 v[112:113], v[116:117], v[112:113]
	v_pk_mul_f32 v[114:115], v[52:53], v[52:53]
	v_pk_mul_f32 v[116:117], v[50:51], v[50:51]
	v_fmac_f32_e32 v42, 0xb9800000, v136
	v_pk_mov_b32 v[118:119], v[116:117], v[114:115] op_sel:[1,0]
	v_mov_b32_e32 v117, v115
	v_fmamk_f32 v43, v136, 0xb9800000, v43
	v_fmac_f32_e32 v44, 0xb9800000, v136
	v_mul_f32_e32 v102, v42, v42
	v_pk_add_f32 v[114:115], v[118:119], v[116:117]
	v_fmamk_f32 v45, v136, 0xb9800000, v45
	v_pk_fma_f32 v[116:117], v[42:43], v[42:43], v[102:103] op_sel_hi:[1,1,0]
	v_mul_f32_e32 v102, v44, v44
	v_pk_add_f32 v[112:113], v[112:113], v[112:113] op_sel_hi:[0,1]
	v_pk_add_f32 v[114:115], v[114:115], v[114:115] op_sel_hi:[0,1]
	v_pk_fma_f32 v[118:119], v[44:45], v[44:45], v[102:103] op_sel_hi:[1,1,0]
	v_fmamk_f32 v81, v136, 0xb9800000, v81
	v_fmac_f32_e32 v80, 0xb9800000, v136
	v_fmamk_f32 v75, v136, 0xb9800000, v75
	v_fmac_f32_e32 v74, 0xb9800000, v136
	v_mul_f32_e32 v116, v74, v74
	v_mul_f32_e32 v118, v75, v75
	v_mul_f32_e32 v114, v80, v80
	v_mul_f32_e32 v112, v81, v81
	v_pk_add_f32 v[116:117], v[116:117], v[118:119]
	v_pk_add_f32 v[112:113], v[114:115], v[112:113]
	v_fmamk_f32 v99, v136, 0xb9800000, v99
	v_fmac_f32_e32 v98, 0xb9800000, v136
	v_fmamk_f32 v101, v136, 0xb9800000, v101
	v_fmac_f32_e32 v100, 0xb9800000, v136
	v_pk_add_f32 v[112:113], v[116:117], v[112:113]
	v_pk_mul_f32 v[114:115], v[100:101], v[100:101]
	v_pk_mul_f32 v[116:117], v[98:99], v[98:99]
	v_fmac_f32_e32 v94, 0xb9800000, v136
	v_pk_mov_b32 v[118:119], v[116:117], v[114:115] op_sel:[1,0]
	v_mov_b32_e32 v117, v115
	v_fmamk_f32 v95, v136, 0xb9800000, v95
	v_fmac_f32_e32 v96, 0xb9800000, v136
	v_mul_f32_e32 v102, v94, v94
	v_pk_add_f32 v[114:115], v[118:119], v[116:117]
	v_fmamk_f32 v97, v136, 0xb9800000, v97
	v_pk_fma_f32 v[116:117], v[94:95], v[94:95], v[102:103] op_sel_hi:[1,1,0]
	v_mul_f32_e32 v102, v96, v96
	v_pk_add_f32 v[112:113], v[112:113], v[112:113] op_sel_hi:[0,1]
	v_pk_add_f32 v[114:115], v[114:115], v[114:115] op_sel_hi:[0,1]
	v_pk_fma_f32 v[118:119], v[96:97], v[96:97], v[102:103] op_sel_hi:[1,1,0]
	v_fmamk_f32 v85, v136, 0xb9800000, v85
	v_fmac_f32_e32 v84, 0xb9800000, v136
	v_fmamk_f32 v83, v136, 0xb9800000, v83
	v_fmac_f32_e32 v82, 0xb9800000, v136
	v_mul_f32_e32 v116, v82, v82
	v_mul_f32_e32 v118, v83, v83
	v_mul_f32_e32 v114, v84, v84
	v_mul_f32_e32 v112, v85, v85
	v_pk_add_f32 v[116:117], v[116:117], v[118:119]
	v_pk_add_f32 v[112:113], v[114:115], v[112:113]
	v_fmamk_f32 v87, v136, 0xb9800000, v87
	v_pk_add_f32 v[112:113], v[116:117], v[112:113]
	v_fmac_f32_e32 v86, 0xb9800000, v136
	v_fmamk_f32 v89, v136, 0xb9800000, v89
	v_fmac_f32_e32 v88, 0xb9800000, v136
	v_pk_add_f32 v[128:129], v[112:113], v[112:113] op_sel_hi:[0,1]
	v_pk_mul_f32 v[112:113], v[88:89], v[88:89]
	v_pk_mul_f32 v[114:115], v[86:87], v[86:87]
	v_fmac_f32_e32 v76, 0xb9800000, v136
	v_pk_mov_b32 v[116:117], v[114:115], v[112:113] op_sel:[1,0]
	v_mov_b32_e32 v115, v113
	v_pk_add_f32 v[112:113], v[116:117], v[114:115]
	v_fmamk_f32 v77, v136, 0xb9800000, v77
	v_pk_add_f32 v[130:131], v[112:113], v[112:113] op_sel_hi:[0,1]
	global_load_dwordx4 v[112:115], v[14:15], off offset:16
	global_load_dwordx4 v[116:119], v[14:15], off
	global_load_dwordx4 v[120:123], v[16:17], off offset:16
	global_load_dwordx4 v[124:127], v[16:17], off
	v_fmac_f32_e32 v78, 0xb9800000, v136
	v_mul_f32_e32 v102, v76, v76
	v_fmamk_f32 v79, v136, 0xb9800000, v79
	v_pk_fma_f32 v[132:133], v[76:77], v[76:77], v[102:103] op_sel_hi:[1,1,0]
	v_mul_f32_e32 v102, v78, v78
	v_pk_fma_f32 v[134:135], v[78:79], v[78:79], v[102:103] op_sel_hi:[1,1,0]
	v_fmamk_f32 v69, v136, 0xb9800000, v69
	v_fmac_f32_e32 v68, 0xb9800000, v136
	v_fmamk_f32 v67, v136, 0xb9800000, v67
	v_fmac_f32_e32 v66, 0xb9800000, v136
	v_mul_f32_e32 v132, v66, v66
	v_mul_f32_e32 v134, v67, v67
; __device__ __forceinline__ void p6_final_ln(const Frame& F) {
;     ...
;         const float mean = wave_sum(s) * (1.f / DM); float q = 0.f;
; #pragma unroll
;         for (int j = 0; j < 16; ++j) { const f32x4 d = z[j] - mean; z[j] = d; q += (d[0] * d[0] + d[1] * d[1]) + (d[2] * d[2] + d[3] * d[3]); }
;         const float rstd = __builtin_amdgcn_rsqf(wave_sum(q) * (1.f / DM) + LN_EPS);
;         float* yr = F.out + (size_t)m * DM;
; #pragma unroll
;         for (int j = 0; j < 8; ++j) { const int col = j * 512 + lane * 8;
;             const f32x4 ga = *(const f32x4*)(F.ln_g + col), gb = *(const f32x4*)(F.ln_g + col + 4), ba = *(const f32x4*)(F.ln_b + col), bb = *(const f32x4*)(F.ln_b + col + 4);
;             *(f32x4*)(yr + col) = z[2 * j] * rstd * ga + ba; *(f32x4*)(yr + col + 4) = z[2 * j + 1] * rstd * gb + bb; }
	v_mul_f32_e32 v130, v68, v68
	v_mul_f32_e32 v128, v69, v69
	v_pk_add_f32 v[132:133], v[132:133], v[134:135]
	v_pk_add_f32 v[128:129], v[130:131], v[128:129]
	v_fmamk_f32 v63, v136, 0xb9800000, v63
	v_fmac_f32_e32 v62, 0xb9800000, v136
	v_fmamk_f32 v65, v136, 0xb9800000, v65
	v_fmac_f32_e32 v64, 0xb9800000, v136
	v_pk_add_f32 v[128:129], v[132:133], v[128:129]
	v_pk_mul_f32 v[130:131], v[64:65], v[64:65]
	v_pk_mul_f32 v[132:133], v[62:63], v[62:63]
	v_fmac_f32_e32 v2, 0xb9800000, v136
	v_pk_mov_b32 v[134:135], v[132:133], v[130:131] op_sel:[1,0]
	v_mov_b32_e32 v133, v131
	v_fmamk_f32 v3, v136, 0xb9800000, v3
	v_fmac_f32_e32 v0, 0xb9800000, v136
	v_mul_f32_e32 v102, v2, v2
	v_pk_add_f32 v[130:131], v[134:135], v[132:133]
	v_fmamk_f32 v1, v136, 0xb9800000, v1
	v_pk_fma_f32 v[132:133], v[2:3], v[2:3], v[102:103] op_sel_hi:[1,1,0]
	v_mul_f32_e32 v102, v0, v0
	v_pk_add_f32 v[128:129], v[128:129], v[128:129] op_sel_hi:[0,1]
	v_pk_add_f32 v[130:131], v[130:131], v[130:131] op_sel_hi:[0,1]
	v_pk_fma_f32 v[134:135], v[0:1], v[0:1], v[102:103] op_sel_hi:[1,1,0]
	v_fmamk_f32 v47, v136, 0xb9800000, v47
	v_fmac_f32_e32 v46, 0xb9800000, v136
	v_fmamk_f32 v49, v136, 0xb9800000, v49
	v_fmac_f32_e32 v48, 0xb9800000, v136
	v_mul_f32_e32 v132, v48, v48
	v_mul_f32_e32 v134, v49, v49
	v_mul_f32_e32 v130, v46, v46
	v_mul_f32_e32 v128, v47, v47
	v_pk_add_f32 v[132:133], v[132:133], v[134:135]
	v_pk_add_f32 v[128:129], v[130:131], v[128:129]
	s_nop 0
	v_pk_add_f32 v[128:129], v[132:133], v[128:129]
	s_nop 0
	v_add_f32_e32 v102, v128, v129
	ds_bpermute_b32 v128, v5, v102
	s_waitcnt lgkmcnt(0)
	v_add_f32_e32 v102, v102, v128
	ds_bpermute_b32 v128, v7, v102
	s_waitcnt lgkmcnt(0)
	v_add_f32_e32 v102, v102, v128
	ds_bpermute_b32 v128, v9, v102
	s_waitcnt lgkmcnt(0)
	v_add_f32_e32 v102, v102, v128
	ds_bpermute_b32 v128, v11, v102
	s_waitcnt lgkmcnt(0)
	v_add_f32_e32 v102, v102, v128
	ds_bpermute_b32 v128, v13, v102
	s_waitcnt lgkmcnt(0)
	v_add_f32_e32 v102, v102, v128
	ds_bpermute_b32 v128, v103, v102
	s_waitcnt lgkmcnt(0)
	v_add_f32_e32 v102, v102, v128
	v_fmamk_f32 v102, v102, 0x39800000, v106
	v_rsq_f32_e32 v102, v102
	s_nop 0
	v_pk_mul_f32 v[128:129], v[92:93], v[102:103] op_sel_hi:[1,0]
	v_pk_mul_f32 v[90:91], v[90:91], v[102:103] op_sel_hi:[1,0]
	v_pk_mul_f32 v[70:71], v[70:71], v[102:103] op_sel_hi:[1,0]
	s_waitcnt vmcnt(0)
	s_barrier
; __device__ __forceinline__ void p6_final_ln(const Frame& F) {
;     ...
;         float* yr = F.out + (size_t)m * DM;
; #pragma unroll
;         for (int j = 0; j < 8; ++j) { const int col = j * 512 + lane * 8;
;             const f32x4 ga = *(const f32x4*)(F.ln_g + col), gb = *(const f32x4*)(F.ln_g + col + 4), ba = *(const f32x4*)(F.ln_b + col), bb = *(const f32x4*)(F.ln_b + col + 4);
;             *(f32x4*)(yr + col) = z[2 * j] * rstd * ga + ba; *(f32x4*)(yr + col + 4) = z[2 * j + 1] * rstd * gb + bb; }
	v_pk_fma_f32 v[92:93], v[118:119], v[90:91], v[126:127]
	v_pk_fma_f32 v[90:91], v[116:117], v[128:129], v[124:125]
	global_store_dwordx4 v109, v[90:93], s[12:13]
	v_pk_mul_f32 v[60:61], v[60:61], v[102:103] op_sel_hi:[1,0]
	v_pk_mul_f32 v[58:59], v[58:59], v[102:103] op_sel_hi:[1,0]
	v_pk_mul_f32 v[90:91], v[72:73], v[102:103] op_sel_hi:[1,0]
	v_pk_fma_f32 v[72:73], v[114:115], v[70:71], v[122:123]
	v_pk_fma_f32 v[70:71], v[112:113], v[90:91], v[120:121]
	global_store_dwordx4 v109, v[70:73], s[12:13] offset:16
	global_load_dwordx4 v[70:73], v[16:17], off offset:2048
	s_nop 0
	global_load_dwordx4 v[90:93], v[14:15], off offset:2048
	global_load_dwordx4 v[112:115], v[14:15], off offset:2064
	global_load_dwordx4 v[116:119], v[16:17], off offset:2064
	v_pk_mul_f32 v[56:57], v[56:57], v[102:103] op_sel_hi:[1,0]
	v_pk_mul_f32 v[54:55], v[54:55], v[102:103] op_sel_hi:[1,0]
	v_pk_mul_f32 v[52:53], v[52:53], v[102:103] op_sel_hi:[1,0]
	v_pk_mul_f32 v[50:51], v[50:51], v[102:103] op_sel_hi:[1,0]
	v_pk_mul_f32 v[44:45], v[44:45], v[102:103] op_sel_hi:[1,0]
	v_pk_mul_f32 v[42:43], v[42:43], v[102:103] op_sel_hi:[1,0]
	v_pk_mul_f32 v[76:77], v[76:77], v[102:103] op_sel_hi:[1,0]
	v_pk_mul_f32 v[68:69], v[68:69], v[102:103] op_sel_hi:[1,0]
	v_pk_mul_f32 v[66:67], v[66:67], v[102:103] op_sel_hi:[1,0]
	v_pk_mul_f32 v[64:65], v[64:65], v[102:103] op_sel_hi:[1,0]
	v_pk_mul_f32 v[62:63], v[62:63], v[102:103] op_sel_hi:[1,0]
	v_pk_mul_f32 v[46:47], v[46:47], v[102:103] op_sel_hi:[1,0]
	v_pk_mul_f32 v[48:49], v[48:49], v[102:103] op_sel_hi:[1,0]
	s_waitcnt vmcnt(2)
	v_pk_fma_f32 v[58:59], v[90:91], v[58:59], v[70:71]
	v_pk_fma_f32 v[60:61], v[92:93], v[60:61], v[72:73]
	s_waitcnt vmcnt(0)
	v_pk_fma_f32 v[54:55], v[112:113], v[54:55], v[116:117]
	v_pk_fma_f32 v[56:57], v[114:115], v[56:57], v[118:119]
	global_store_dwordx4 v109, v[58:61], s[12:13] offset:2048
	global_store_dwordx4 v109, v[54:57], s[12:13] offset:2064
	global_load_dwordx4 v[54:57], v[20:21], off
	s_nop 0
	global_load_dwordx4 v[58:61], v[18:19], off
	global_load_dwordx4 v[70:73], v[18:19], off offset:16
	global_load_dwordx4 v[90:93], v[20:21], off offset:16
	s_waitcnt vmcnt(2)
	v_pk_fma_f32 v[50:51], v[58:59], v[50:51], v[54:55]
	v_pk_fma_f32 v[52:53], v[60:61], v[52:53], v[56:57]
	s_waitcnt vmcnt(0)
	v_pk_fma_f32 v[42:43], v[70:71], v[42:43], v[90:91]
	v_pk_fma_f32 v[44:45], v[72:73], v[44:45], v[92:93]
	global_store_dwordx4 v104, v[50:53], s[12:13]
	global_store_dwordx4 v104, v[42:45], s[12:13] offset:16
	global_load_dwordx4 v[42:45], v[24:25], off
	s_nop 0
	global_load_dwordx4 v[50:53], v[22:23], off
	global_load_dwordx4 v[54:57], v[22:23], off offset:16
	global_load_dwordx4 v[58:61], v[24:25], off offset:16
	v_pk_mul_f32 v[70:71], v[80:81], v[102:103] op_sel_hi:[1,0]
	v_pk_mul_f32 v[72:73], v[74:75], v[102:103] op_sel_hi:[1,0]
	v_pk_mul_f32 v[74:75], v[84:85], v[102:103] op_sel_hi:[1,0]
	v_pk_mul_f32 v[80:81], v[82:83], v[102:103] op_sel_hi:[1,0]
	s_waitcnt vmcnt(2)
	v_pk_fma_f32 v[42:43], v[50:51], v[72:73], v[42:43]
	v_pk_fma_f32 v[44:45], v[52:53], v[70:71], v[44:45]
	global_store_dwordx4 v105, v[42:45], s[12:13]
	v_pk_mul_f32 v[70:71], v[96:97], v[102:103] op_sel_hi:[1,0]
	v_pk_mul_f32 v[72:73], v[94:95], v[102:103] op_sel_hi:[1,0]
	v_pk_mul_f32 v[44:45], v[100:101], v[102:103] op_sel_hi:[1,0]
	v_pk_mul_f32 v[42:43], v[98:99], v[102:103] op_sel_hi:[1,0]
	s_waitcnt vmcnt(1)
	v_pk_fma_f32 v[44:45], v[56:57], v[44:45], v[60:61]
	v_pk_fma_f32 v[42:43], v[54:55], v[42:43], v[58:59]
	global_store_dwordx4 v105, v[42:45], s[12:13] offset:16
	global_load_dwordx4 v[42:45], v[28:29], off
	s_nop 0
	global_load_dwordx4 v[50:53], v[26:27], off
	global_load_dwordx4 v[54:57], v[26:27], off offset:16
	global_load_dwordx4 v[58:61], v[28:29], off offset:16
	s_waitcnt vmcnt(2)
	v_pk_fma_f32 v[42:43], v[50:51], v[72:73], v[42:43]
	v_pk_fma_f32 v[44:45], v[52:53], v[70:71], v[44:45]
	s_waitcnt vmcnt(0)
	v_pk_fma_f32 v[50:51], v[54:55], v[80:81], v[58:59]
	v_pk_fma_f32 v[52:53], v[56:57], v[74:75], v[60:61]
	global_store_dwordx4 v107, v[42:45], s[12:13]
	global_store_dwordx4 v107, v[50:53], s[12:13] offset:16
	global_load_dwordx4 v[42:45], v[32:33], off
	s_nop 0
	global_load_dwordx4 v[50:53], v[30:31], off
	global_load_dwordx4 v[54:57], v[30:31], off offset:16
	global_load_dwordx4 v[58:61], v[32:33], off offset:16
	v_pk_mul_f32 v[70:71], v[88:89], v[102:103] op_sel_hi:[1,0]
	v_pk_mul_f32 v[72:73], v[86:87], v[102:103] op_sel_hi:[1,0]
	v_pk_mul_f32 v[74:75], v[78:79], v[102:103] op_sel_hi:[1,0]
	s_waitcnt vmcnt(2)
	v_pk_fma_f32 v[42:43], v[50:51], v[72:73], v[42:43]
	v_pk_fma_f32 v[44:45], v[52:53], v[70:71], v[44:45]
	s_waitcnt vmcnt(0)
	v_pk_fma_f32 v[50:51], v[54:55], v[76:77], v[58:59]
	v_pk_fma_f32 v[52:53], v[56:57], v[74:75], v[60:61]
	global_store_dwordx4 v108, v[42:45], s[12:13]
	global_store_dwordx4 v108, v[50:53], s[12:13] offset:16
	global_load_dwordx4 v[42:45], v[36:37], off
	s_nop 0
	global_load_dwordx4 v[50:53], v[34:35], off
	global_load_dwordx4 v[54:57], v[34:35], off offset:16
	global_load_dwordx4 v[58:61], v[36:37], off offset:16
	s_waitcnt vmcnt(2)
	v_pk_fma_f32 v[42:43], v[50:51], v[66:67], v[42:43]
	v_pk_fma_f32 v[44:45], v[52:53], v[68:69], v[44:45]
	s_waitcnt vmcnt(0)
	v_pk_fma_f32 v[50:51], v[54:55], v[62:63], v[58:59]
	v_pk_fma_f32 v[52:53], v[56:57], v[64:65], v[60:61]
	global_store_dwordx4 v111, v[42:45], s[12:13]
	global_store_dwordx4 v111, v[50:53], s[12:13] offset:16
	global_load_dwordx4 v[42:45], v[40:41], off
	s_nop 0
	global_load_dwordx4 v[50:53], v[38:39], off
	global_load_dwordx4 v[54:57], v[38:39], off offset:16
	global_load_dwordx4 v[58:61], v[40:41], off offset:16
	v_pk_mul_f32 v[62:63], v[0:1], v[102:103] op_sel_hi:[1,0]
	v_pk_mul_f32 v[0:1], v[2:3], v[102:103] op_sel_hi:[1,0]
	s_waitcnt vmcnt(2)
	v_pk_fma_f32 v[2:3], v[52:53], v[62:63], v[44:45]
	v_pk_fma_f32 v[0:1], v[50:51], v[0:1], v[42:43]
	s_waitcnt vmcnt(0)
	v_pk_fma_f32 v[42:43], v[48:49], v[54:55], v[58:59]
	v_pk_fma_f32 v[44:45], v[46:47], v[56:57], v[60:61]
	global_store_dwordx4 v110, v[0:3], s[12:13]
	global_store_dwordx4 v110, v[42:45], s[12:13] offset:16
	s_cbranch_scc0 .LBB0_578
